# register hand-off across a barrier: waves 4-7 compute the four Wp row tiles of their own value tile directly into the solve stage's accumulator registers (no Wp LDS write/read)
# speedup vs baseline: 1.0136x; 1.0125x over previous
.LBB0_385:
	s_waitcnt lgkmcnt(0)
	s_barrier
	s_waitcnt lgkmcnt(0)
	v_readfirstlane_b32 s26, v0
	s_lshr_b32 s26, s26, 6
	s_cmp_lt_u32 s26, 4
	s_cbranch_scc1 .Lp5_skip
	s_lshr_b32 s27, s26, 1
	s_mul_i32 s27, s27, 0xa00
	v_subrev_u32_e32 v27, s27, v224
	s_and_b32 s27, s26, 1
	s_lshl_b32 s27, s27, 1
	s_sub_i32 s28, s26, s27
	s_add_i32 s28, s28, -4
	s_mul_i32 s28, s28, 0x900
	v_add_u32_e32 v28, s28, v225
	ds_read_b128 v[94:97], v28
	ds_read_b128 v[102:105], v27 offset:16384
	ds_read_b128 v[106:109], v27 offset:18944
	ds_read_b128 v[140:143], v27 offset:21504
	ds_read_b128 v[148:151], v27 offset:24064
	ds_read_b128 v[98:101], v28 offset:64
	ds_read_b128 v[144:147], v27 offset:21568
	ds_read_b128 v[152:155], v27 offset:24128
	s_waitcnt lgkmcnt(6)
	v_mfma_f32_16x16x32_bf16 v[66:69], v[102:105], v[94:97], 0
	s_waitcnt lgkmcnt(5)
	v_mfma_f32_16x16x32_bf16 v[90:93], v[106:109], v[94:97], 0
	s_waitcnt lgkmcnt(4)
	v_mfma_f32_16x16x32_bf16 v[86:89], v[140:143], v[94:97], 0
	s_waitcnt lgkmcnt(3)
	v_mfma_f32_16x16x32_bf16 v[82:85], v[148:151], v[94:97], 0
	s_waitcnt lgkmcnt(1)
	v_mfma_f32_16x16x32_bf16 v[86:89], v[144:147], v[98:101], v[86:89]
	s_waitcnt lgkmcnt(0)
	v_mfma_f32_16x16x32_bf16 v[82:85], v[152:155], v[98:101], v[82:85]
	s_nop 1
	v_mov_b32_e32 v48, v66
	v_mov_b32_e32 v49, v67
	s_branch .LBB0_391

.LBB0_391:
	s_waitcnt lgkmcnt(0)
	s_barrier
	v_add_u32_e32 v26, 0x1800, v213
	ds_read2st64_b64 v[78:81], v213 offset0:5 offset1:10
	ds_read2_b64 v[70:73], v26 offset0:192 offset1:196
	ds_read_b64 v[76:77], v213 offset:5152
	ds_read_b64 v[66:67], v213 offset:7744
	s_mov_b64 s[26:27], -1
	s_and_b64 vcc, exec, s[4:5]
	s_cbranch_vccz .LBB0_393
	s_mov_b64 s[26:27], 0
